# W1Z transpose on phase 8's 128 idle workgroups (last half round) + W1OUT transpose inside the split ptanh barrier; phase 9 after rwkv2 has no transposes left
# speedup vs baseline: 1.0008x; 1.0008x over previous
; __device__ __forceinline__ u32x4 pack8(const float* f) { u32x4 w; w.x = pk2(f[0], f[1]); w.y = pk2(f[2], f[3]); w.z = pk2(f[4], f[5]); w.w = pk2(f[6], f[7]); return w; }
; __device__ void tconv(unsigned char* smem, const float* src, int ldsrc, int col0, int N, int K, u16* dst, int ldd) {
;     ...
;     for (; tile < ntile; tile += gridDim.x) {
;         const int tn = tile % tilesN, tk = tile / tilesN;
; #pragma unroll
;         for (int j = 0; j < 4; ++j) { T[lr * 65 + lc + j] = v0[j]; T[(lr + 32) * 65 + lc + j] = v1[j]; }
;         asm volatile("s_waitcnt lgkmcnt(0)" ::: "memory"); __builtin_amdgcn_s_barrier(); asm volatile("" ::: "memory");
;         const int nx = tile + gridDim.x;
;         if (nx < ntile) { const int tn2 = nx % tilesN, tk2 = nx / tilesN; const float* s = src + (size_t)(tk2 * 64 + lr) * ldsrc + col0 + tn2 * 64 + lc;
;             v0 = __builtin_nontemporal_load((const f32x4*)s); v1 = __builtin_nontemporal_load((const f32x4*)(s + (size_t)32 * ldsrc)); }
;         float f[8];
; #pragma unroll
;         for (int j = 0; j < 8; ++j) f[j] = T[(sk + j) * 65 + sn];
;         *(u32x4*)(dst + (size_t)(tn * 64 + sn) * ldd + tk * 64 + sk) = pack8(f);
;         asm volatile("s_waitcnt lgkmcnt(0)" ::: "memory"); __builtin_amdgcn_s_barrier(); asm volatile("" ::: "memory");
;     }
;     __syncthreads();
TCV5_noload:
	ds_read2_b32 v[156:157], v149 offset1:65
	ds_read2_b32 v[158:159], v149 offset0:130 offset1:195
	ds_read2_b32 v[160:161], v150 offset0:4 offset1:69
	ds_read2_b32 v[162:163], v150 offset0:134 offset1:199
	ds_read2_b32 v[164:165], v151 offset1:65
	ds_read2_b32 v[166:167], v151 offset0:130 offset1:195
	ds_read2_b32 v[168:169], v152 offset0:4 offset1:69
	ds_read2_b32 v[170:171], v152 offset0:134 offset1:199
	v_add_u32_e32 v154, s50, v144
	v_add_u32_e32 v155, s51, v144
	s_waitcnt lgkmcnt(7)
	v_cvt_pk_bf16_f32 v156, v156, v157
	s_waitcnt lgkmcnt(6)
	v_cvt_pk_bf16_f32 v157, v158, v159
	s_waitcnt lgkmcnt(5)
	v_cvt_pk_bf16_f32 v158, v160, v161
	s_waitcnt lgkmcnt(4)
	v_cvt_pk_bf16_f32 v159, v162, v163
	global_store_dwordx4 v154, v[156:159], s[44:45]
	s_waitcnt lgkmcnt(3)
	v_cvt_pk_bf16_f32 v164, v164, v165
	s_waitcnt lgkmcnt(2)
	v_cvt_pk_bf16_f32 v165, v166, v167
	s_waitcnt lgkmcnt(1)
	v_cvt_pk_bf16_f32 v166, v168, v169
	s_waitcnt lgkmcnt(0)
	v_cvt_pk_bf16_f32 v167, v170, v171
	global_store_dwordx4 v155, v[164:167], s[44:45]
	s_barrier
	s_cmpk_lt_i32 s46, 0x800
	s_waitcnt vmcnt(2)
	s_cbranch_scc1 TCV5_body
	s_waitcnt lgkmcnt(0)
	s_barrier

; __device__ void tconv(unsigned char* smem, const float* src, int ldsrc, int col0, int N, int K, u16* dst, int ldd) {
;     float* T = (float*)smem;
;     const int tid = threadIdx.x, tilesN = N >> 6, ntile = tilesN * (K >> 6);
;     const int lr = tid >> 4, lc = (tid & 15) * 4;
;     const int sn = tid >> 3, sk = (tid & 7) * 8;
;     int tile = blockIdx.x;
;     f32x4 v0 = {0.f, 0.f, 0.f, 0.f}, v1 = {0.f, 0.f, 0.f, 0.f};
;     if (tile < ntile) { const int tn = tile % tilesN, tk = tile / tilesN; const float* s = src + (size_t)(tk * 64 + lr) * ldsrc + col0 + tn * 64 + lc;
;         v0 = __builtin_nontemporal_load((const f32x4*)s); v1 = __builtin_nontemporal_load((const f32x4*)(s + (size_t)32 * ldsrc)); }
;     for (; tile < ntile; tile += gridDim.x) {
;         const int tn = tile % tilesN, tk = tile / tilesN;
; #pragma unroll
;         for (int j = 0; j < 4; ++j) { T[lr * 65 + lc + j] = v0[j]; T[(lr + 32) * 65 + lc + j] = v1[j]; }
;         asm volatile("s_waitcnt lgkmcnt(0)" ::: "memory"); __builtin_amdgcn_s_barrier(); asm volatile("" ::: "memory");
;         const int nx = tile + gridDim.x;
;         if (nx < ntile) { const int tn2 = nx % tilesN, tk2 = nx / tilesN; const float* s = src + (size_t)(tk2 * 64 + lr) * ldsrc + col0 + tn2 * 64 + lc;
;             v0 = __builtin_nontemporal_load((const f32x4*)s); v1 = __builtin_nontemporal_load((const f32x4*)(s + (size_t)32 * ldsrc)); }
SPLIT9_tconv:
	s_or_b64 exec, exec, s[0:1]
	s_cmpk_gt_i32 s70, 0x7ff
	s_cbranch_scc1 SPLIT9_notc
	s_waitcnt vmcnt(0) lgkmcnt(0)
	s_barrier
	v_readlane_b32 s40, v250, 15
	v_readlane_b32 s41, v250, 16
	v_and_b32_e32 v142, 0x3ff, v0
	v_lshrrev_b32_e32 v153, 4, v142
	v_and_b32_e32 v154, 15, v142
	v_lshlrev_b32_e32 v154, 4, v154
	v_lshlrev_b32_e32 v143, 13, v153
	v_add_u32_e32 v143, v143, v154
	v_mul_u32_u24_e32 v145, 0x104, v153
	v_add_u32_e32 v145, v145, v154
	v_add_u32_e32 v146, 0x2080, v145
	v_add_u32_e32 v147, 0x4100, v145
	v_add_u32_e32 v148, 0x6180, v145
	v_lshrrev_b32_e32 v153, 3, v142
	v_and_b32_e32 v154, 7, v142
	v_mul_u32_u24_e32 v149, 0x820, v154
	v_lshl_add_u32 v149, v153, 2, v149
	v_add_u32_e32 v150, 0x400, v149
	v_add_u32_e32 v151, 0x4100, v149
	v_add_u32_e32 v152, 0x4500, v149
	v_lshlrev_b32_e32 v144, 13, v153
	v_lshl_add_u32 v144, v154, 4, v144
	s_add_u32 s44, s64, 0x1d000000
	s_addc_u32 s45, s65, 0
	s_lshl_b32 s54, s62, 1
	s_mov_b32 s46, s70
	s_waitcnt lgkmcnt(0)
	s_add_u32 s42, s40, 0x40000
	s_addc_u32 s43, s41, 0
	s_add_i32 s47, s46, s62
	s_cmpk_lt_i32 s47, 0x800
	s_cselect_b32 s47, s47, s46
	s_and_b32 s52, s46, 0x1f
	s_lshr_b32 s53, s46, 5
	s_lshl_b32 s52, s52, 8
	s_lshl_b32 s53, s53, 19
	s_add_i32 s48, s52, s53
	s_and_b32 s52, s47, 0x1f
	s_lshr_b32 s53, s47, 5
	s_lshl_b32 s52, s52, 8
	s_lshl_b32 s53, s53, 19
	s_add_i32 s49, s52, s53
	v_add_u32_e32 v153, s48, v143
	v_add_u32_e32 v172, s49, v143
	global_load_dwordx4 v[70:73], v153, s[40:41] nt
	global_load_dwordx4 v[74:77], v153, s[42:43] nt
	global_load_dwordx4 v[78:81], v172, s[40:41] nt
	global_load_dwordx4 v[82:85], v172, s[42:43] nt
	s_waitcnt vmcnt(0)
